# as v64, plus WIN of layer 1 converted during layer 0's scan into the unused XLO slot; layer 1's projection GEMMs read B from there (spill-lane redirect)
# baseline (speedup 1.0000x reference)
.LBB0_76:
	s_mov_b32 s98, 0
	s_mov_b32 s17, 0x1
	s_cmp_eq_u32 s88, 0
	s_cbranch_scc1 .LBB0_81
	s_mov_b32 s17, 0
	s_mov_b32 s99, 0
	s_cmp_eq_u32 s88, 8
	s_cbranch_scc0 .Lcv_nordr
	s_add_u32 s99, s86, 0x3680000
	s_addc_u32 s100, s87, 0
	s_nop 0
	v_writelane_b32 v252, s99, 39
	v_writelane_b32 v252, s100, 40
	s_add_u32 s99, s86, 0x3d80000
	s_addc_u32 s100, s87, 0
	s_nop 0
	v_writelane_b32 v252, s99, 23
	v_writelane_b32 v252, s100, 24
	s_mov_b32 s99, 0
.Lcv_nordr:
	s_cmp_eq_u32 s88, 1
	s_cselect_b32 s17, 0x6, s17
	s_cselect_b32 s99, 0x96, s99
	s_cmp_eq_u32 s17, 0
	s_cbranch_scc1 .LBB0_78
	s_cmp_lt_u32 s2, s99
	s_cbranch_scc0 .Lcv_idle

.Lcv_noproc:
	s_mov_b32 s34, 0
	s_lshl_b32 s54, s12, 10
	s_add_i32 s54, s54, s53
	s_mov_b32 s55, 0x2500
	s_cmp_eq_u32 s30, 0
	s_cselect_b32 s55, 0x6700, s55
	s_cmp_lt_u32 s54, s55
	s_cbranch_scc0 .Lcv_noitem
	s_lshl_b32 s61, s30, 12
	s_cmp_lt_u32 s54, 0x400
	s_cbranch_scc0 .Lcv_j1
	v_readlane_b32 s58, v255, 17
	v_readlane_b32 s59, v255, 18
	s_lshl_b32 s4, s30, 22
	s_mov_b32 s60, 0x2100000
	s_mov_b32 s57, 0
	s_branch .Lcv_jsel

.Lcv_j4:
	s_cmp_lt_u32 s54, 0x4600
	s_cbranch_scc0 .Lcv_j5
	s_sub_u32 s54, s54, 0x3b00
	v_readlane_b32 s58, v254, 51
	v_readlane_b32 s59, v254, 52
	s_mov_b32 s4, 0xb00000
	s_mov_b32 s60, 0xb00000
	s_mov_b32 s57, 2
	s_branch .Lcv_jsel
.Lcv_j5:
	s_sub_u32 s54, s54, 0x4600
	v_readlane_b32 s58, v254, 55
	v_readlane_b32 s59, v254, 56
	v_readlane_b32 s6, v254, 53
	v_readlane_b32 s7, v254, 54
	s_mov_b32 s4, 0x2100000
	s_mov_b32 s60, 0x3680000
	s_mov_b32 s57, 3
	s_nop 1
	s_add_u32 s6, s6, 0x1000
	s_addc_u32 s7, s7, 0
.Lcv_jsel:
	s_nop 1
	s_add_u32 s58, s58, s4
	s_addc_u32 s59, s59, 0
	s_cmp_eq_u32 s57, 1
	s_cbranch_scc1 .Lcv_shb
	s_cmp_eq_u32 s57, 3
	s_cbranch_scc1 .Lcv_shd
	s_and_b32 s55, s54, 63
	s_lshr_b32 s56, s54, 6
	s_lshl_b32 s0, s55, 4
	s_mov_b32 s1, 0x1000
	s_mov_b32 s5, 0xb00
	s_cmp_eq_u32 s57, 0
	s_cselect_b32 s5, 0x400, s5
	s_mov_b32 s35, 0
	s_branch .Lcv_shdone
.Lcv_shb:
	s_lshr_b32 s56, s54, 5
	s_mul_i32 s56, s56, 0xba2f
	s_lshr_b32 s56, s56, 19
	s_mul_i32 s55, s56, 0x160
	s_sub_u32 s55, s54, s55
	s_lshl_b32 s0, s55, 4
	s_lshr_b32 s1, s0, 8
	s_lshl_b32 s1, s1, 7
	s_and_b32 s5, s0, 0x7f
	s_add_i32 s1, s1, s5
	s_and_b32 s5, s0, 0x80
	s_cmp_lg_u32 s5, 0
	s_cselect_b32 s5, 0xb00, 0
	s_add_i32 s0, s1, s5
	s_mov_b32 s1, 0x5800
	s_mov_b32 s5, 0x400
	s_mov_b32 s35, 1
	s_branch .Lcv_shdone
.Lcv_shd:
	s_lshr_b32 s56, s54, 4
	s_mul_i32 s56, s56, 0x7c20
	s_lshr_b32 s56, s56, 20
	s_mul_i32 s55, s56, 0x210
	s_sub_u32 s55, s54, s55
	s_lshl_b32 s0, s55, 4
	s_cmp_lt_u32 s0, 0xd00
	s_cbranch_scc1 .Lcv_m2done
	s_sub_u32 s1, s0, 0xd00
	s_lshr_b32 s4, s1, 8
	s_and_b32 s5, s1, 0xff
	s_cmp_lt_u32 s4, 4
	s_cbranch_scc0 .Lcv_m2b
	s_lshl_b32 s0, s4, 8
	s_add_i32 s0, s0, s5
	s_add_i32 s0, s0, 0x1900
	s_branch .Lcv_m2done
.Lcv_m2b:
	s_and_b32 s1, s5, 0x7f
	s_and_b32 s5, s5, 0x80
	s_cmp_lt_u32 s4, 12
	s_cbranch_scc0 .Lcv_m2c
	s_sub_u32 s4, s4, 4
	s_lshl_b32 s4, s4, 7
	s_add_i32 s1, s1, s4
	s_mov_b32 s0, 0x1d00
	s_cmp_lg_u32 s5, 0
	s_cselect_b32 s0, 0xd00, s0
	s_add_i32 s0, s0, s1
	s_branch .Lcv_m2done
.Lcv_m2c:
	s_sub_u32 s4, s4, 12
	s_lshl_b32 s4, s4, 7
	s_add_i32 s1, s1, s4
	s_mov_b32 s0, 0x1100
	s_cmp_lg_u32 s5, 0
	s_cselect_b32 s0, 0x1500, s0
	s_add_i32 s0, s0, s1
.Lcv_m2done:
	s_mov_b32 s1, 0x8400
	s_mov_b32 s5, 0x400
	s_mov_b32 s35, 1

.LBB0_606:
	s_and_b64 vcc, exec, s[0:1]
	s_cbranch_vccz .LBB0_508
	s_waitcnt vmcnt(0)
	v_lshrrev_b32_e32 v90, 4, v241
	v_bfe_u32 v91, v241, 3, 1
	v_and_b32_e32 v86, 15, v241
	v_lshlrev_b32_e32 v90, 1, v90
	v_lshlrev_b32_e32 v86, 4, v86
	v_add_u32_e32 v92, v90, v91
	v_xor_b32_e32 v91, 1, v91
	v_add_u32_e32 v93, v90, v91
	s_lshl_b32 s0, s10, 5
	v_lshlrev_b32_e32 v89, 2, v92
	v_add_u32_e32 v92, s0, v92
	v_add_u32_e32 v93, s0, v93
	v_add_u32_e32 v89, 0x18000, v89
	v_lshlrev_b32_e32 v87, 2, v92
	v_lshlrev_b32_e32 v88, 2, v93
	v_mov_b32_e32 v0, 0
	v_mov_b32_e32 v1, 0
	v_mov_b32_e32 v2, 0
	v_mov_b32_e32 v3, 0
	v_mov_b32_e32 v4, 0
	v_mov_b32_e32 v5, 0
	v_mov_b32_e32 v6, 0
	v_mov_b32_e32 v7, 0
	s_waitcnt lgkmcnt(0)
	s_barrier
	s_mov_b32 s4, 0
	s_nop 0
	s_nop 0
	s_nop 0
	s_nop 0
	s_nop 0
	s_nop 0
	s_nop 0
	s_nop 0
